# attn loop: counted vmcnt ladder (4/2/1/0) instead of vmcnt(0) before the half-1 staging ds_writes, so each write waits only for its own global load
# speedup vs baseline: 1.0083x; 1.0004x over previous
; __device__ __forceinline__ void finishSM(f32x16& p0, f32x16& p1, float alpha, float& l_reg, bf16x8& pa0, bf16x8& pa1, bf16x8& pa2, bf16x8& pa3) {
; #pragma unroll
;   for (int r = 0; r < 16; ++r) p1[r] = __builtin_amdgcn_exp2f(p1[r]);
;   float ps = 0;
; #pragma unroll
;   for (int r = 0; r < 16; ++r) ps += p0[r];
; #pragma unroll
;   for (int r = 0; r < 16; ++r) ps += p1[r];
;   { auto rr = __builtin_amdgcn_permlane32_swap(__float_as_uint(ps), __float_as_uint(ps), false, false);
;     ps = __uint_as_float(rr[0]) + __uint_as_float(rr[1]); }
;   l_reg = l_reg * alpha + ps;
;     ...
;   PK4(p0, 0, pa0); PK4(p0, 8, pa1); PK4(p1, 0, pa2); PK4(p1, 8, pa3);
;     ...
; }
; __device__ __forceinline__ void qkt(f32x16& p0, f32x16& p1, const char* Ks, const bf16x8* qr, const char* qrl, int r32, int hi) {
;   p0 = f32x16{}; p1 = f32x16{};
; #pragma unroll
;   for (int d0 = 0; d0 < 8; ++d0) { int cb = (d0 * 16 + hi * 8) * 2;
;     bf16x8 b0 = *reinterpret_cast<const bf16x8*>(Ks + KSWZ(r32, cb));
;     bf16x8 b1 = *reinterpret_cast<const bf16x8*>(Ks + KSWZ(32 + r32, cb));
;     p0 = __builtin_amdgcn_mfma_f32_32x32x16_bf16(b0, qr[d0], p0, 0, 0, 0);
;     p1 = __builtin_amdgcn_mfma_f32_32x32x16_bf16(b1, qr[d0], p1, 0, 0, 0); }
; #pragma unroll
;   for (int d0 = 8; d0 < 12; ++d0) { int cb = (d0 * 16 + hi * 8) * 2;
;     bf16x8 b0 = *reinterpret_cast<const bf16x8*>(Ks + KSWZ(r32, cb));
;     bf16x8 b1 = *reinterpret_cast<const bf16x8*>(Ks + KSWZ(32 + r32, cb));
;     bf16x8 qf = *reinterpret_cast<const bf16x8*>(qrl + (((2 * (d0 - 8) + hi) ^ ((r32 >> 1) & 7)) << 4));
;     p0 = __builtin_amdgcn_mfma_f32_32x32x16_bf16(b0, qf, p0, 0, 0, 0);
;     p1 = __builtin_amdgcn_mfma_f32_32x32x16_bf16(b1, qf, p1, 0, 0, 0); }
; }
.Lattn_steady:
	v_exp_f32_e32 v225, v225
	v_exp_f32_e32 v228, v228
	v_exp_f32_e32 v226, v226
	v_add_f32_e32 v211, v225, v228
	s_waitcnt lgkmcnt(3)
	v_mfma_f32_32x32x16_bf16 v[80:95], v[236:239], v[124:127], 0
	ds_read_b128 v[236:239], v206 offset:49152
	v_exp_f32_e32 v229, v229
	v_add_f32_e32 v211, v226, v211
	v_exp_f32_e32 v227, v227
	v_add_f32_e32 v211, v229, v211
	v_mfma_f32_32x32x16_bf16 v[64:79], v[240:243], v[124:127], 0
	ds_read_b128 v[240:243], v208 offset:36864
	v_exp_f32_e32 v230, v230
	v_add_f32_e32 v211, v227, v211
	v_exp_f32_e32 v223, v223
	v_add_f32_e32 v211, v230, v211
	s_waitcnt lgkmcnt(3)
	v_mfma_f32_32x32x16_bf16 v[80:95], v[248:251], v[120:123], v[80:95]
	ds_read_b128 v[248:251], v208 offset:49152
	v_exp_f32_e32 v224, v224
	v_add_f32_e32 v211, v223, v211
	v_exp_f32_e32 v219, v219
	v_add_f32_e32 v211, v224, v211
	v_mfma_f32_32x32x16_bf16 v[64:79], v[244:247], v[120:123], v[64:79]
	ds_read_b128 v[244:247], v207 offset:36864
	v_exp_f32_e32 v221, v221
	v_add_f32_e32 v211, v219, v211
	v_exp_f32_e32 v220, v220
	v_add_f32_e32 v211, v221, v211
	s_waitcnt lgkmcnt(3)
	v_mfma_f32_32x32x16_bf16 v[80:95], v[232:235], v[116:119], v[80:95]
	ds_read_b128 v[232:235], v207 offset:49152
	v_exp_f32_e32 v222, v222
	v_add_f32_e32 v211, v220, v211
	v_exp_f32_e32 v215, v215
	v_add_f32_e32 v211, v222, v211
	v_mfma_f32_32x32x16_bf16 v[64:79], v[236:239], v[116:119], v[64:79]
	ds_read_b128 v[236:239], v204 offset:36864
	v_exp_f32_e32 v217, v217
	v_add_f32_e32 v211, v215, v211
	v_exp_f32_e32 v216, v216
	v_add_f32_e32 v211, v217, v211
	s_waitcnt lgkmcnt(3)
	v_mfma_f32_32x32x16_bf16 v[80:95], v[240:243], v[112:115], v[80:95]
	ds_read_b128 v[240:243], v204 offset:49152
	v_exp_f32_e32 v218, v218
	v_add_f32_e32 v211, v216, v211
	v_exp_f32_e32 v162, v162
	v_add_f32_e32 v211, v218, v211
	v_mfma_f32_32x32x16_bf16 v[64:79], v[248:251], v[112:115], v[64:79]
	ds_read_b128 v[248:251], v203 offset:36864
	v_exp_f32_e32 v163, v163
	v_exp_f32_e32 v160, v160
	v_exp_f32_e32 v161, v161
	s_waitcnt lgkmcnt(3)
	v_mfma_f32_32x32x16_bf16 v[80:95], v[244:247], v[108:111], v[80:95]
	ds_read_b128 v[244:247], v203 offset:49152
	v_exp_f32_e32 v158, v158
	v_exp_f32_e32 v159, v159
	v_exp_f32_e32 v156, v156
	v_mfma_f32_32x32x16_bf16 v[64:79], v[232:235], v[108:111], v[64:79]
	ds_read_b128 v[232:235], v200 offset:36864
	v_exp_f32_e32 v157, v157
	v_exp_f32_e32 v154, v154
	v_exp_f32_e32 v155, v155
	s_waitcnt lgkmcnt(3)
	v_mfma_f32_32x32x16_bf16 v[80:95], v[236:239], v[104:107], v[80:95]
	ds_read_b128 v[236:239], v200 offset:49152
	v_exp_f32_e32 v152, v152
	v_exp_f32_e32 v153, v153
	v_exp_f32_e32 v150, v150
	v_mfma_f32_32x32x16_bf16 v[64:79], v[240:243], v[104:107], v[64:79]
	ds_read_b128 v[240:243], v191 offset:36864
	v_exp_f32_e32 v151, v151
	v_exp_f32_e32 v148, v148
	v_exp_f32_e32 v149, v149
	s_waitcnt lgkmcnt(3)
	v_mfma_f32_32x32x16_bf16 v[80:95], v[248:251], v[100:103], v[80:95]
	ds_read_b128 v[248:251], v202 offset:49152
	v_add_f32_e32 v212, v162, v163
	v_add_f32_e32 v212, v160, v212
	v_add_f32_e32 v212, v161, v212
	v_add_f32_e32 v212, v158, v212
	v_add_f32_e32 v212, v159, v212
	v_add_f32_e32 v212, v156, v212
	v_mfma_f32_32x32x16_bf16 v[64:79], v[244:247], v[100:103], v[64:79]
	ds_read_b128 v[244:247], v182
	v_add_f32_e32 v212, v157, v212
	v_add_f32_e32 v212, v154, v212
	v_add_f32_e32 v212, v155, v212
	v_add_f32_e32 v212, v152, v212
	v_add_f32_e32 v212, v153, v212
	v_add_f32_e32 v212, v150, v212
	s_waitcnt lgkmcnt(3)
	v_mfma_f32_32x32x16_bf16 v[80:95], v[232:235], v[96:99], v[80:95]
	ds_read_b128 v[232:235], v198 offset:36864
	v_add_f32_e32 v212, v151, v212
	v_add_f32_e32 v212, v148, v212
	v_add_f32_e32 v212, v149, v212
	v_add_f32_e32 v211, v211, v212
	v_mov_b32_e32 v212, v211
	s_lshl_b32 s19, s18, 14
	v_add_u32_e32 v231, s19, v183
	s_waitcnt vmcnt(4)
	v_mfma_f32_32x32x16_bf16 v[64:79], v[236:239], v[96:99], v[64:79]
	ds_read_b128 v[236:239], v201 offset:49152
	ds_write_b128 v231, v[140:143]
	v_add_u32_e32 v140, s19, v184
	s_waitcnt vmcnt(2)
	ds_write_b128 v140, v[144:147]
	ds_write_b128 v185, v[136:139] offset:12288
	s_waitcnt vmcnt(1)
	ds_write_b128 v185, v[132:135] offset:24576
	s_mov_b32 s18, 0xfffa0000
	s_waitcnt lgkmcnt(6)
	v_mfma_f32_32x32x16_bf16 v[80:95], v[240:243], v[244:247], v[80:95]
	ds_read_b128 v[240:243], v181
	s_waitcnt vmcnt(0)
; __device__ __forceinline__ void partialSM(f32x16& p0, f32x16& p1, float& m_reg, float& mn, float& alpha) {
;     ...
;   for (int r = 1; r < 16; ++r) pmax = fmaxf(pmax, p0[r]);
; #pragma unroll
;   for (int r = 0; r < 16; ++r) pmax = fmaxf(pmax, p1[r]);
;   { auto rr = __builtin_amdgcn_permlane32_swap(__float_as_uint(pmax), __float_as_uint(pmax), false, false);
;     pmax = fmaxf(__uint_as_float(rr[0]), __uint_as_float(rr[1])); }
;   if (__builtin_expect(__all(pmax - m_reg <= THR / SCALE), 1)) { mn = m_reg; alpha = 1.f; }
;   else { mn = fmaxf(m_reg, pmax); alpha = __builtin_amdgcn_exp2f((m_reg - mn) * C); m_reg = mn; }
;   float mnC = -mn * C;
; #pragma unroll
;   for (int r = 0; r < 16; ++r) p0[r] = fmaf(p0[r], C, mnC);
; #pragma unroll
;   for (int r = 0; r < 16; ++r) p1[r] = fmaf(p1[r], C, mnC);
; #pragma unroll
;   for (int r = 0; r < 16; ++r) p0[r] = __builtin_amdgcn_exp2f(p0[r]);
; }
; __device__ __forceinline__ void finishSM(f32x16& p0, f32x16& p1, float alpha, float& l_reg, bf16x8& pa0, bf16x8& pa1, bf16x8& pa2, bf16x8& pa3) {
; #pragma unroll
;   for (int r = 0; r < 16; ++r) p1[r] = __builtin_amdgcn_exp2f(p1[r]);
;   float ps = 0;
; #pragma unroll
;   for (int r = 0; r < 16; ++r) ps += p0[r];
; #pragma unroll
;   for (int r = 0; r < 16; ++r) ps += p1[r];
;   { auto rr = __builtin_amdgcn_permlane32_swap(__float_as_uint(ps), __float_as_uint(ps), false, false);
;     ps = __uint_as_float(rr[0]) + __uint_as_float(rr[1]); }
;   l_reg = l_reg * alpha + ps;
;     ...
;   PK4(p0, 0, pa0); PK4(p0, 8, pa1); PK4(p1, 0, pa2); PK4(p1, 8, pa3);
;     ...
; }
; __device__ __forceinline__ void qkt(f32x16& p0, f32x16& p1, const char* Ks, const bf16x8* qr, const char* qrl, int r32, int hi) {
;   p0 = f32x16{}; p1 = f32x16{};
; #pragma unroll
;   for (int d0 = 0; d0 < 8; ++d0) { int cb = (d0 * 16 + hi * 8) * 2;
;     bf16x8 b0 = *reinterpret_cast<const bf16x8*>(Ks + KSWZ(r32, cb));
;     bf16x8 b1 = *reinterpret_cast<const bf16x8*>(Ks + KSWZ(32 + r32, cb));
;     p0 = __builtin_amdgcn_mfma_f32_32x32x16_bf16(b0, qr[d0], p0, 0, 0, 0);
;     p1 = __builtin_amdgcn_mfma_f32_32x32x16_bf16(b1, qr[d0], p1, 0, 0, 0); }
; #pragma unroll
;   for (int d0 = 8; d0 < 12; ++d0) { int cb = (d0 * 16 + hi * 8) * 2;
;     bf16x8 b0 = *reinterpret_cast<const bf16x8*>(Ks + KSWZ(r32, cb));
;     bf16x8 b1 = *reinterpret_cast<const bf16x8*>(Ks + KSWZ(32 + r32, cb));
	ds_write_b128 v186, v[128:131] offset:12288
	v_add_co_u32_e32 v128, vcc, s18, v168
	s_mov_b32 s18, 0xfffc0000
	s_nop 0
	v_addc_co_u32_e32 v129, vcc, -1, v169, vcc
	v_add_co_u32_e32 v130, vcc, s18, v168
	s_movk_i32 s18, 0xe000
	s_nop 0
	v_addc_co_u32_e32 v131, vcc, -1, v169, vcc
	v_mfma_f32_32x32x16_bf16 v[64:79], v[248:251], v[244:247], v[64:79]
	ds_read_b128 v[248:251], v187 offset:36864
	ds_read_b128 v[244:247], v189 offset:49152
	global_load_dwordx4 v[140:143], v[128:129], off
	global_load_dwordx4 v[136:139], v[128:129], off offset:-256
	global_load_dwordx4 v[144:147], v[130:131], off
	global_load_dwordx4 v[132:135], v[130:131], off offset:-256
	v_add_co_u32_e32 v128, vcc, s18, v166
	s_nop 1
	v_addc_co_u32_e32 v129, vcc, -1, v167, vcc
	s_waitcnt lgkmcnt(3)
	v_mfma_f32_32x32x16_bf16 v[80:95], v[232:235], v[240:243], v[80:95]
	ds_read_b128 v[232:235], v179
	global_load_dwordx4 v[128:131], v[128:129], off
	v_cvt_pk_bf16_f32 v158, v158, v159
	v_cvt_pk_bf16_f32 v159, v156, v157
	v_permlane32_swap_b32_e32 v211, v212
	v_cvt_pk_bf16_f32 v156, v162, v163
	v_cvt_pk_bf16_f32 v157, v160, v161
	v_mfma_f32_32x32x16_bf16 v[64:79], v[236:239], v[240:243], v[64:79]
	ds_read_b128 v[236:239], v188 offset:36864
	ds_read_b128 v[240:243], v190 offset:49152
	v_cvt_pk_bf16_f32 v160, v154, v155
	v_cvt_pk_bf16_f32 v161, v152, v153
	v_cvt_pk_bf16_f32 v162, v150, v151
	v_cvt_pk_bf16_f32 v163, v148, v149
	v_add_f32_e32 v211, v211, v212
	v_cvt_pk_bf16_f32 v148, v225, v228
	s_waitcnt lgkmcnt(2)
	v_mfma_f32_32x32x16_bf16 v[80:95], v[248:251], v[232:235], v[80:95]
	ds_read_b128 v[248:251], v177
	v_cvt_pk_bf16_f32 v149, v226, v229
	v_cvt_pk_bf16_f32 v150, v227, v230
	v_cvt_pk_bf16_f32 v151, v223, v224
	v_cvt_pk_bf16_f32 v152, v219, v221
	v_cvt_pk_bf16_f32 v153, v220, v222
	v_cvt_pk_bf16_f32 v154, v215, v217
	v_mfma_f32_32x32x16_bf16 v[64:79], v[244:247], v[232:235], v[64:79]
	v_cvt_pk_bf16_f32 v155, v216, v218
	v_fma_f32 v176, v209, v176, v211
	s_waitcnt lgkmcnt(0)
	v_mfma_f32_32x32x16_bf16 v[80:95], v[236:239], v[248:251], v[80:95]
	v_mfma_f32_32x32x16_bf16 v[64:79], v[240:243], v[248:251], v[64:79]
	s_lshl_b32 s31, s30, 14
	v_add_u32_e32 v180, s31, v178
	ds_read_b64_tr_b16 v[232:233], v180 offset:0
	ds_read_b64_tr_b16 v[234:235], v180 offset:2048
	ds_read_b64_tr_b16 v[236:237], v180 offset:512
	ds_read_b64_tr_b16 v[238:239], v180 offset:2560
	ds_read_b64_tr_b16 v[240:241], v180 offset:1024
	ds_read_b64_tr_b16 v[242:243], v180 offset:3072
	ds_read_b64_tr_b16 v[248:249], v180 offset:1536
	ds_read_b64_tr_b16 v[250:251], v180 offset:3584
	ds_read_b64_tr_b16 v[244:245], v180 offset:4096
	ds_read_b64_tr_b16 v[246:247], v180 offset:6144
	s_nop 3
	v_max3_f32 v194, v80, v81, v82
	v_max3_f32 v195, v64, v65, v66
	v_max3_f32 v194, v194, v83, v84
	v_max3_f32 v195, v195, v67, v68
	s_waitcnt lgkmcnt(6)
	v_mfma_f32_32x32x16_bf16 v[32:47], v[148:151], v[232:235], v[32:47]
	ds_read_b64_tr_b16 v[232:233], v180 offset:4608
	ds_read_b64_tr_b16 v[234:235], v180 offset:6656
	v_max3_f32 v194, v194, v85, v86
	v_max3_f32 v195, v195, v69, v70
	v_max3_f32 v194, v194, v87, v88
	v_max3_f32 v195, v195, v71, v72
	v_mfma_f32_32x32x16_bf16 v[48:63], v[148:151], v[236:239], v[48:63]
	ds_read_b64_tr_b16 v[236:237], v180 offset:5120
	ds_read_b64_tr_b16 v[238:239], v180 offset:7168
	v_max3_f32 v194, v194, v89, v90
	v_max3_f32 v195, v195, v73, v74
	v_max3_f32 v194, v194, v91, v92
	v_max3_f32 v195, v195, v75, v76
	s_waitcnt lgkmcnt(6)
	v_mfma_f32_32x32x16_bf16 v[16:31], v[148:151], v[240:243], v[16:31]
	ds_read_b64_tr_b16 v[240:241], v180 offset:5632
	ds_read_b64_tr_b16 v[242:243], v180 offset:7680
	v_max3_f32 v194, v194, v93, v94
	v_max3_f32 v195, v195, v77, v78
	v_max3_f32 v194, v194, v95, v195
	v_max_f32_e32 v194, v194, v79
	v_mfma_f32_32x32x16_bf16 v[0:15], v[148:151], v[248:251], v[0:15]
	ds_read_b64_tr_b16 v[248:249], v180 offset:8192
	ds_read_b64_tr_b16 v[250:251], v180 offset:10240
	v_mov_b32_e32 v195, v194
	s_nop 1
	v_permlane32_swap_b32_e32 v194, v195
	v_max_f32_e32 v194, v194, v195
	s_waitcnt lgkmcnt(6)
	v_mfma_f32_32x32x16_bf16 v[32:47], v[152:155], v[244:247], v[32:47]
	ds_read_b64_tr_b16 v[244:245], v180 offset:8704
	ds_read_b64_tr_b16 v[246:247], v180 offset:10752
	v_sub_f32_e32 v195, v194, v210
	v_cmp_ge_f32_e32 vcc, s15, v195
	v_mfma_f32_32x32x16_bf16 v[48:63], v[152:155], v[232:235], v[48:63]
	ds_read_b64_tr_b16 v[232:233], v180 offset:9216
	ds_read_b64_tr_b16 v[234:235], v180 offset:11264
	s_cmp_eq_u64 vcc, exec
	s_cselect_b64 s[40:41], -1, 0
	s_cbranch_scc1 .Lattn_fast1
	v_max_f32_e32 v194, v210, v194
	v_sub_f32_e32 v195, v210, v194
	v_mul_f32_e32 v195, 0x3dd53b94, v195
	v_exp_f32_e32 v214, v195
	v_mov_b32_e32 v210, v194
	s_branch .Lattn_join1
